# nt (non-temporal) hint on the read-once f32 input loads: phase-0 rmsnorm loads and the WOUT epilogue's f32 residual loads
# speedup vs baseline: 1.0202x; 1.0202x over previous
.LBB0_173:
	v_add_u32_e32 v18, 0xffff0000, v94
	v_ashrrev_i32_e32 v95, 31, v94
	v_cmp_gt_i32_e32 vcc, s21, v94
	v_add_u32_e32 v88, s90, v94
	v_cmp_gt_i32_e64 s[6:7], s18, v88
	v_cndmask_b32_e32 v19, 0, v95, vcc
	v_cndmask_b32_e32 v18, v18, v94, vcc
	v_cndmask_b32_e32 v21, v100, v101, vcc
	v_cndmask_b32_e32 v20, v102, v103, vcc
	v_lshlrev_b64 v[18:19], 12, v[18:19]
	v_lshl_add_u64 v[18:19], v[20:21], 0, v[18:19]
	v_lshl_add_u64 v[18:19], v[18:19], 0, v[84:85]
	global_load_dwordx4 v[78:81], v[18:19], off nt
	global_load_dwordx4 v[74:77], v[18:19], off offset:1024 nt
	global_load_dwordx4 v[70:73], v[18:19], off offset:2048 nt
	global_load_dwordx4 v[62:65], v[18:19], off offset:3072 nt
	v_ashrrev_i32_e32 v89, 31, v88
	v_mov_b32_e32 v38, 0
	v_mov_b32_e32 v39, 0
	v_mov_b32_e32 v40, 0
	v_mov_b32_e32 v41, 0
	v_mov_b32_e32 v50, 0
	v_mov_b32_e32 v51, 0
	v_mov_b32_e32 v52, 0
	v_mov_b32_e32 v53, 0
	v_mov_b32_e32 v58, 0
	v_mov_b32_e32 v59, 0
	v_mov_b32_e32 v60, 0
	v_mov_b32_e32 v61, 0
	v_mov_b32_e32 v66, 0
	v_mov_b32_e32 v67, 0
	v_mov_b32_e32 v68, 0
	v_mov_b32_e32 v69, 0
	s_and_saveexec_b64 s[4:5], s[6:7]
	s_cbranch_execz .LBB0_175
	v_add_u32_e32 v18, 0xffff0000, v88
	v_cmp_gt_i32_e32 vcc, s21, v88
	v_mov_b32_e32 v20, s15
	v_mov_b32_e32 v21, s13
	v_cndmask_b32_e32 v19, 0, v89, vcc
	v_cndmask_b32_e32 v18, v18, v88, vcc
	v_cndmask_b32_e32 v21, v20, v21, vcc
	v_mov_b32_e32 v20, s14
	v_mov_b32_e32 v22, s12
	v_cndmask_b32_e32 v20, v20, v22, vcc
	v_lshlrev_b64 v[18:19], 12, v[18:19]
	v_lshl_add_u64 v[18:19], v[20:21], 0, v[18:19]
	v_lshl_add_u64 v[18:19], v[18:19], 0, v[84:85]
	global_load_dwordx4 v[66:69], v[18:19], off nt
	global_load_dwordx4 v[58:61], v[18:19], off offset:1024 nt
	global_load_dwordx4 v[50:53], v[18:19], off offset:2048 nt
	global_load_dwordx4 v[38:41], v[18:19], off offset:3072 nt
.LBB0_175:
	s_or_b64 exec, exec, s[4:5]
	v_add_u32_e32 v92, s19, v94
	v_cmp_gt_i32_e64 s[4:5], s18, v92
	v_mov_b32_e32 v18, 0
	v_ashrrev_i32_e32 v93, 31, v92
	v_mov_b32_e32 v26, 0
	s_waitcnt lgkmcnt(0)
	v_mov_b32_e32 v27, 0
	v_mov_b32_e32 v28, 0
	v_mov_b32_e32 v29, 0
	v_mov_b32_e32 v34, 0
	v_mov_b32_e32 v35, 0
	v_mov_b32_e32 v36, 0
	v_mov_b32_e32 v37, 0
	v_mov_b32_e32 v46, 0
	v_mov_b32_e32 v47, 0
	v_mov_b32_e32 v48, 0
	v_mov_b32_e32 v49, 0
	v_mov_b32_e32 v54, 0
	v_mov_b32_e32 v55, 0
	v_mov_b32_e32 v56, 0
	v_mov_b32_e32 v57, 0
	s_and_saveexec_b64 s[8:9], s[4:5]
	s_cbranch_execz .LBB0_177
	v_add_u32_e32 v19, 0xffff0000, v92
	v_cmp_gt_i32_e32 vcc, s21, v92
	v_mov_b32_e32 v22, s13
	s_nop 0
	v_cndmask_b32_e32 v20, v19, v92, vcc
	v_mov_b32_e32 v19, s15
	v_cndmask_b32_e32 v21, 0, v93, vcc
	v_cndmask_b32_e32 v23, v19, v22, vcc
	v_mov_b32_e32 v19, s14
	v_mov_b32_e32 v22, s12
	v_cndmask_b32_e32 v22, v19, v22, vcc
	v_lshlrev_b64 v[20:21], 12, v[20:21]
	v_lshl_add_u64 v[20:21], v[22:23], 0, v[20:21]
	v_lshl_add_u64 v[20:21], v[20:21], 0, v[84:85]
	global_load_dwordx4 v[54:57], v[20:21], off nt
	global_load_dwordx4 v[46:49], v[20:21], off offset:1024 nt
	global_load_dwordx4 v[34:37], v[20:21], off offset:2048 nt
	global_load_dwordx4 v[26:29], v[20:21], off offset:3072 nt
.LBB0_177:
	s_or_b64 exec, exec, s[8:9]
	v_add_u32_e32 v90, s20, v94
	v_cmp_gt_i32_e32 vcc, s18, v90
	v_ashrrev_i32_e32 v91, 31, v90
	v_mov_b32_e32 v19, 0
	v_mov_b32_e32 v20, 0
	v_mov_b32_e32 v21, 0
	v_mov_b32_e32 v22, 0
	v_mov_b32_e32 v23, 0
	v_mov_b32_e32 v24, 0
	v_mov_b32_e32 v25, 0
	v_mov_b32_e32 v30, 0
	v_mov_b32_e32 v31, 0
	v_mov_b32_e32 v32, 0
	v_mov_b32_e32 v33, 0
	v_mov_b32_e32 v42, 0
	v_mov_b32_e32 v43, 0
	v_mov_b32_e32 v44, 0
	v_mov_b32_e32 v45, 0
	s_and_saveexec_b64 s[16:17], vcc
	s_cbranch_execz .LBB0_179
	v_add_u32_e32 v18, 0xffff0000, v90
	v_cmp_gt_i32_e64 s[8:9], s21, v90
	v_mov_b32_e32 v20, s15
	v_mov_b32_e32 v21, s13
	v_cndmask_b32_e64 v19, 0, v91, s[8:9]
	v_cndmask_b32_e64 v18, v18, v90, s[8:9]
	v_cndmask_b32_e64 v21, v20, v21, s[8:9]
	v_mov_b32_e32 v20, s14
	v_mov_b32_e32 v22, s12
	v_cndmask_b32_e64 v20, v20, v22, s[8:9]
	v_lshlrev_b64 v[18:19], 12, v[18:19]
	v_lshl_add_u64 v[18:19], v[20:21], 0, v[18:19]
	v_lshl_add_u64 v[106:107], v[18:19], 0, v[84:85]
	global_load_dwordx4 v[42:45], v[106:107], off nt
	global_load_dwordx4 v[30:33], v[106:107], off offset:1024 nt
	global_load_dwordx4 v[22:25], v[106:107], off offset:2048 nt
	global_load_dwordx4 v[18:21], v[106:107], off offset:3072 nt

.LBB0_1439:
	s_bitcmp1_b32 s101, 6
	s_cbranch_scc1 .Lqepi_6
	v_and_b32_e32 v128, 63, v180
	v_and_b32_e32 v129, 15, v180
	v_bfe_u32 v130, v180, 4, 2
	v_lshrrev_b32_e32 v131, 6, v180
	v_lshlrev_b32_e32 v131, 12, v131
	v_add_u32_e32 v131, 0x20000, v131
	v_and_b32_e32 v132, 7, v129
	v_xor_b32_e32 v132, v130, v132
	v_lshlrev_b32_e32 v132, 4, v132
	v_lshl_add_u32 v132, v129, 8, v132
	v_add_u32_e32 v169, v131, v132
	v_xor_b32_e32 v170, 64, v169
	v_lshrrev_b32_e32 v133, 2, v128
	v_and_b32_e32 v134, 3, v128
	v_and_b32_e32 v135, 7, v133
	v_lshlrev_b32_e32 v136, 1, v134
	v_xor_b32_e32 v136, v136, v135
	v_lshlrev_b32_e32 v136, 4, v136
	v_lshl_add_u32 v136, v133, 8, v136
	v_add_u32_e32 v171, v131, v136
	v_xor_b32_e32 v172, 16, v171
	s_lshl_b32 s9, s34, 20
	s_cmp_lt_u32 s34, 0x100
	s_cselect_b32 s98, s12, s14
	s_cselect_b32 s99, s13, s15
	s_cselect_b32 s9, s9, 0
	s_add_u32 s98, s98, s9
	s_addc_u32 s99, s99, 0
	v_add_u32_e32 v137, s54, v133
	v_lshlrev_b32_e32 v137, 12, v137
	s_lshl_b32 s9, s8, 8
	s_add_i32 s9, s9, s55
	v_lshl_add_u32 v138, v134, 3, s9
	v_lshl_add_u32 v175, v138, 2, v137
	s_lshl_b32 s9, s34, 8
	s_add_i32 s9, s9, s54
	v_add_u32_e32 v139, s9, v133
	v_lshlrev_b32_e32 v174, 2, v139
	v_lshlrev_b32_e32 v139, 11, v139
	v_lshl_add_u32 v173, v138, 1, v139
	v_cmp_eq_u32_e32 vcc, 0, v134
	global_load_dwordx4 v[188:191], v175, s[98:99] nt
	global_load_dwordx4 v[192:195], v175, s[98:99] offset:16 nt
	global_load_dwordx4 v[196:199], v175, s[98:99] offset:512 nt
	global_load_dwordx4 v[200:203], v175, s[98:99] offset:528 nt
	s_add_u32 s98, s98, 0x10000
	s_addc_u32 s99, s99, 0
	global_load_dwordx4 v[204:207], v175, s[98:99] nt
	global_load_dwordx4 v[208:211], v175, s[98:99] offset:16 nt
	global_load_dwordx4 v[212:215], v175, s[98:99] offset:512 nt
	global_load_dwordx4 v[216:219], v175, s[98:99] offset:528 nt
	s_add_u32 s98, s98, 0x10000
	s_addc_u32 s99, s99, 0
	global_load_dwordx4 v[220:223], v175, s[98:99] nt
	global_load_dwordx4 v[224:227], v175, s[98:99] offset:16 nt
	global_load_dwordx4 v[228:231], v175, s[98:99] offset:512 nt
	global_load_dwordx4 v[232:235], v175, s[98:99] offset:528 nt
	s_add_u32 s98, s98, 0x10000
	s_addc_u32 s99, s99, 0
	global_load_dwordx4 v[236:239], v175, s[98:99] nt
	global_load_dwordx4 v[240:243], v175, s[98:99] offset:16 nt
	global_load_dwordx4 v[244:247], v175, s[98:99] offset:512 nt
	global_load_dwordx4 v[248:251], v175, s[98:99] offset:528 nt
	s_add_u32 s98, s98, 0x50000
	s_addc_u32 s99, s99, 0
	s_mov_b64 s[8:9], exec
	ds_write_b128 v169, v[124:127]
	ds_write_b128 v170, v[120:123]
	ds_write_b128 v169, v[116:119] offset:128
	ds_write_b128 v170, v[112:115] offset:128
	s_waitcnt lgkmcnt(0)
	ds_read_b128 v[128:131], v171
	ds_read_b128 v[132:135], v172
	ds_read_b128 v[136:139], v171 offset:128
	ds_read_b128 v[140:143], v172 offset:128
	s_waitcnt lgkmcnt(0)
	ds_write_b128 v169, v[108:111]
	ds_write_b128 v170, v[104:107]
	ds_write_b128 v169, v[100:103] offset:128
	ds_write_b128 v170, v[96:99] offset:128
	s_waitcnt vmcnt(12)
	v_pk_add_f32 v[128:129], v[128:129], v[188:189]
	v_pk_add_f32 v[130:131], v[130:131], v[190:191]
	v_pk_add_f32 v[132:133], v[132:133], v[192:193]
	v_pk_add_f32 v[134:135], v[134:135], v[194:195]
	v_pk_mul_f32 v[176:177], v[128:129], v[128:129]
	v_pk_fma_f32 v[176:177], v[130:131], v[130:131], v[176:177]
	v_pk_fma_f32 v[176:177], v[132:133], v[132:133], v[176:177]
	v_pk_fma_f32 v[176:177], v[134:135], v[134:135], v[176:177]
	v_cvt_pk_bf16_f32 v156, v128, v129
	v_cvt_pk_bf16_f32 v157, v130, v131
	v_cvt_pk_bf16_f32 v158, v132, v133
	v_cvt_pk_bf16_f32 v159, v134, v135
	global_store_dwordx4 v173, v[156:159], s[16:17]
	v_pk_add_f32 v[136:137], v[136:137], v[196:197]
	v_pk_add_f32 v[138:139], v[138:139], v[198:199]
	v_pk_add_f32 v[140:141], v[140:141], v[200:201]
	v_pk_add_f32 v[142:143], v[142:143], v[202:203]
	v_pk_fma_f32 v[176:177], v[136:137], v[136:137], v[176:177]
	v_pk_fma_f32 v[176:177], v[138:139], v[138:139], v[176:177]
	v_pk_fma_f32 v[176:177], v[140:141], v[140:141], v[176:177]
	v_pk_fma_f32 v[176:177], v[142:143], v[142:143], v[176:177]
	v_cvt_pk_bf16_f32 v160, v136, v137
	v_cvt_pk_bf16_f32 v161, v138, v139
	v_cvt_pk_bf16_f32 v162, v140, v141
	v_cvt_pk_bf16_f32 v163, v142, v143
	global_store_dwordx4 v173, v[160:163], s[16:17] offset:256
	v_add_f32_e32 v178, v176, v177
	s_nop 1
	v_add_f32_dpp v179, v178, v178 quad_perm:[1,0,3,2] row_mask:0xf bank_mask:0xf
	s_nop 1
	v_add_f32_dpp v181, v179, v179 quad_perm:[2,3,0,1] row_mask:0xf bank_mask:0xf
	s_mov_b64 exec, vcc
	global_atomic_add_f32 v174, v181, s[18:19] offset:0
	s_mov_b64 exec, s[8:9]
	global_load_dwordx4 v[188:191], v175, s[98:99] nt
	global_load_dwordx4 v[192:195], v175, s[98:99] offset:16 nt
	global_load_dwordx4 v[196:199], v175, s[98:99] offset:512 nt
	global_load_dwordx4 v[200:203], v175, s[98:99] offset:528 nt
	s_add_u32 s98, s98, 0x10000
	s_addc_u32 s99, s99, 0
	v_add_u32_e32 v173, 0x8000, v173
	s_waitcnt lgkmcnt(0)
	ds_read_b128 v[128:131], v171
	ds_read_b128 v[132:135], v172
	ds_read_b128 v[136:139], v171 offset:128
	ds_read_b128 v[140:143], v172 offset:128
	s_waitcnt lgkmcnt(0)
	ds_write_b128 v169, v[92:95]
	ds_write_b128 v170, v[88:91]
	ds_write_b128 v169, v[84:87] offset:128
	ds_write_b128 v170, v[80:83] offset:128
	s_waitcnt vmcnt(15)
	v_pk_add_f32 v[128:129], v[128:129], v[204:205]
	v_pk_add_f32 v[130:131], v[130:131], v[206:207]
	v_pk_add_f32 v[132:133], v[132:133], v[208:209]
	v_pk_add_f32 v[134:135], v[134:135], v[210:211]
	v_pk_mul_f32 v[176:177], v[128:129], v[128:129]
	v_pk_fma_f32 v[176:177], v[130:131], v[130:131], v[176:177]
	v_pk_fma_f32 v[176:177], v[132:133], v[132:133], v[176:177]
	v_pk_fma_f32 v[176:177], v[134:135], v[134:135], v[176:177]
	v_cvt_pk_bf16_f32 v156, v128, v129
	v_cvt_pk_bf16_f32 v157, v130, v131
	v_cvt_pk_bf16_f32 v158, v132, v133
	v_cvt_pk_bf16_f32 v159, v134, v135
	global_store_dwordx4 v173, v[156:159], s[16:17]
	v_pk_add_f32 v[136:137], v[136:137], v[212:213]
	v_pk_add_f32 v[138:139], v[138:139], v[214:215]
	v_pk_add_f32 v[140:141], v[140:141], v[216:217]
	v_pk_add_f32 v[142:143], v[142:143], v[218:219]
	v_pk_fma_f32 v[176:177], v[136:137], v[136:137], v[176:177]
	v_pk_fma_f32 v[176:177], v[138:139], v[138:139], v[176:177]
	v_pk_fma_f32 v[176:177], v[140:141], v[140:141], v[176:177]
	v_pk_fma_f32 v[176:177], v[142:143], v[142:143], v[176:177]
	v_cvt_pk_bf16_f32 v160, v136, v137
	v_cvt_pk_bf16_f32 v161, v138, v139
	v_cvt_pk_bf16_f32 v162, v140, v141
	v_cvt_pk_bf16_f32 v163, v142, v143
	global_store_dwordx4 v173, v[160:163], s[16:17] offset:256
	v_add_f32_e32 v178, v176, v177
	s_nop 1
	v_add_f32_dpp v179, v178, v178 quad_perm:[1,0,3,2] row_mask:0xf bank_mask:0xf
	s_nop 1
	v_add_f32_dpp v181, v179, v179 quad_perm:[2,3,0,1] row_mask:0xf bank_mask:0xf
	s_mov_b64 exec, vcc
	global_atomic_add_f32 v174, v181, s[18:19] offset:64
	s_mov_b64 exec, s[8:9]
	global_load_dwordx4 v[204:207], v175, s[98:99] nt
	global_load_dwordx4 v[208:211], v175, s[98:99] offset:16 nt
	global_load_dwordx4 v[212:215], v175, s[98:99] offset:512 nt
	global_load_dwordx4 v[216:219], v175, s[98:99] offset:528 nt
	s_add_u32 s98, s98, 0x10000
	s_addc_u32 s99, s99, 0
	v_add_u32_e32 v173, 0x8000, v173
	s_waitcnt lgkmcnt(0)
	ds_read_b128 v[128:131], v171
	ds_read_b128 v[132:135], v172
	ds_read_b128 v[136:139], v171 offset:128
	ds_read_b128 v[140:143], v172 offset:128
	s_waitcnt lgkmcnt(0)
	ds_write_b128 v169, v[76:79]
	ds_write_b128 v170, v[72:75]
	ds_write_b128 v169, v[68:71] offset:128
	ds_write_b128 v170, v[64:67] offset:128
	s_waitcnt vmcnt(18)
	v_pk_add_f32 v[128:129], v[128:129], v[220:221]
	v_pk_add_f32 v[130:131], v[130:131], v[222:223]
	v_pk_add_f32 v[132:133], v[132:133], v[224:225]
	v_pk_add_f32 v[134:135], v[134:135], v[226:227]
	v_pk_mul_f32 v[176:177], v[128:129], v[128:129]
	v_pk_fma_f32 v[176:177], v[130:131], v[130:131], v[176:177]
	v_pk_fma_f32 v[176:177], v[132:133], v[132:133], v[176:177]
	v_pk_fma_f32 v[176:177], v[134:135], v[134:135], v[176:177]
	v_cvt_pk_bf16_f32 v156, v128, v129
	v_cvt_pk_bf16_f32 v157, v130, v131
	v_cvt_pk_bf16_f32 v158, v132, v133
	v_cvt_pk_bf16_f32 v159, v134, v135
	global_store_dwordx4 v173, v[156:159], s[16:17]
	v_pk_add_f32 v[136:137], v[136:137], v[228:229]
	v_pk_add_f32 v[138:139], v[138:139], v[230:231]
	v_pk_add_f32 v[140:141], v[140:141], v[232:233]
	v_pk_add_f32 v[142:143], v[142:143], v[234:235]
	v_pk_fma_f32 v[176:177], v[136:137], v[136:137], v[176:177]
	v_pk_fma_f32 v[176:177], v[138:139], v[138:139], v[176:177]
	v_pk_fma_f32 v[176:177], v[140:141], v[140:141], v[176:177]
	v_pk_fma_f32 v[176:177], v[142:143], v[142:143], v[176:177]
	v_cvt_pk_bf16_f32 v160, v136, v137
	v_cvt_pk_bf16_f32 v161, v138, v139
	v_cvt_pk_bf16_f32 v162, v140, v141
	v_cvt_pk_bf16_f32 v163, v142, v143
	global_store_dwordx4 v173, v[160:163], s[16:17] offset:256
	v_add_f32_e32 v178, v176, v177
	s_nop 1
	v_add_f32_dpp v179, v178, v178 quad_perm:[1,0,3,2] row_mask:0xf bank_mask:0xf
	s_nop 1
	v_add_f32_dpp v181, v179, v179 quad_perm:[2,3,0,1] row_mask:0xf bank_mask:0xf
	s_mov_b64 exec, vcc
	global_atomic_add_f32 v174, v181, s[18:19] offset:128
	s_mov_b64 exec, s[8:9]
	global_load_dwordx4 v[220:223], v175, s[98:99] nt
	global_load_dwordx4 v[224:227], v175, s[98:99] offset:16 nt
	global_load_dwordx4 v[228:231], v175, s[98:99] offset:512 nt
	global_load_dwordx4 v[232:235], v175, s[98:99] offset:528 nt
	s_add_u32 s98, s98, 0x10000
	s_addc_u32 s99, s99, 0
	v_add_u32_e32 v173, 0x8000, v173
	s_waitcnt lgkmcnt(0)
	ds_read_b128 v[128:131], v171
	ds_read_b128 v[132:135], v172
	ds_read_b128 v[136:139], v171 offset:128
	ds_read_b128 v[140:143], v172 offset:128
	s_waitcnt lgkmcnt(0)
	ds_write_b128 v169, v[60:63]
	ds_write_b128 v170, v[56:59]
	ds_write_b128 v169, v[52:55] offset:128
	ds_write_b128 v170, v[48:51] offset:128
	s_waitcnt vmcnt(21)
	v_pk_add_f32 v[128:129], v[128:129], v[236:237]
	v_pk_add_f32 v[130:131], v[130:131], v[238:239]
	v_pk_add_f32 v[132:133], v[132:133], v[240:241]
	v_pk_add_f32 v[134:135], v[134:135], v[242:243]
	v_pk_mul_f32 v[176:177], v[128:129], v[128:129]
	v_pk_fma_f32 v[176:177], v[130:131], v[130:131], v[176:177]
	v_pk_fma_f32 v[176:177], v[132:133], v[132:133], v[176:177]
	v_pk_fma_f32 v[176:177], v[134:135], v[134:135], v[176:177]
	v_cvt_pk_bf16_f32 v156, v128, v129
	v_cvt_pk_bf16_f32 v157, v130, v131
	v_cvt_pk_bf16_f32 v158, v132, v133
	v_cvt_pk_bf16_f32 v159, v134, v135
	global_store_dwordx4 v173, v[156:159], s[16:17]
	v_pk_add_f32 v[136:137], v[136:137], v[244:245]
	v_pk_add_f32 v[138:139], v[138:139], v[246:247]
	v_pk_add_f32 v[140:141], v[140:141], v[248:249]
	v_pk_add_f32 v[142:143], v[142:143], v[250:251]
	v_pk_fma_f32 v[176:177], v[136:137], v[136:137], v[176:177]
	v_pk_fma_f32 v[176:177], v[138:139], v[138:139], v[176:177]
	v_pk_fma_f32 v[176:177], v[140:141], v[140:141], v[176:177]
	v_pk_fma_f32 v[176:177], v[142:143], v[142:143], v[176:177]
	v_cvt_pk_bf16_f32 v160, v136, v137
	v_cvt_pk_bf16_f32 v161, v138, v139
	v_cvt_pk_bf16_f32 v162, v140, v141
	v_cvt_pk_bf16_f32 v163, v142, v143
	global_store_dwordx4 v173, v[160:163], s[16:17] offset:256
	v_add_f32_e32 v178, v176, v177
	s_nop 1
	v_add_f32_dpp v179, v178, v178 quad_perm:[1,0,3,2] row_mask:0xf bank_mask:0xf
	s_nop 1
	v_add_f32_dpp v181, v179, v179 quad_perm:[2,3,0,1] row_mask:0xf bank_mask:0xf
	s_mov_b64 exec, vcc
	global_atomic_add_f32 v174, v181, s[18:19] offset:192
	s_mov_b64 exec, s[8:9]
	global_load_dwordx4 v[236:239], v175, s[98:99] nt
	global_load_dwordx4 v[240:243], v175, s[98:99] offset:16 nt
	global_load_dwordx4 v[244:247], v175, s[98:99] offset:512 nt
	global_load_dwordx4 v[248:251], v175, s[98:99] offset:528 nt
	v_add_u32_e32 v173, 0x28000, v173
	s_waitcnt lgkmcnt(0)
	ds_read_b128 v[128:131], v171
	ds_read_b128 v[132:135], v172
	ds_read_b128 v[136:139], v171 offset:128
	ds_read_b128 v[140:143], v172 offset:128
	s_waitcnt lgkmcnt(0)
	ds_write_b128 v169, v[44:47]
	ds_write_b128 v170, v[40:43]
	ds_write_b128 v169, v[36:39] offset:128
	ds_write_b128 v170, v[32:35] offset:128
	s_waitcnt vmcnt(21)
	v_pk_add_f32 v[128:129], v[128:129], v[188:189]
	v_pk_add_f32 v[130:131], v[130:131], v[190:191]
	v_pk_add_f32 v[132:133], v[132:133], v[192:193]
	v_pk_add_f32 v[134:135], v[134:135], v[194:195]
	v_pk_mul_f32 v[176:177], v[128:129], v[128:129]
	v_pk_fma_f32 v[176:177], v[130:131], v[130:131], v[176:177]
	v_pk_fma_f32 v[176:177], v[132:133], v[132:133], v[176:177]
	v_pk_fma_f32 v[176:177], v[134:135], v[134:135], v[176:177]
	v_cvt_pk_bf16_f32 v156, v128, v129
	v_cvt_pk_bf16_f32 v157, v130, v131
	v_cvt_pk_bf16_f32 v158, v132, v133
	v_cvt_pk_bf16_f32 v159, v134, v135
	global_store_dwordx4 v173, v[156:159], s[16:17]
	v_pk_add_f32 v[136:137], v[136:137], v[196:197]
	v_pk_add_f32 v[138:139], v[138:139], v[198:199]
	v_pk_add_f32 v[140:141], v[140:141], v[200:201]
	v_pk_add_f32 v[142:143], v[142:143], v[202:203]
	v_pk_fma_f32 v[176:177], v[136:137], v[136:137], v[176:177]
	v_pk_fma_f32 v[176:177], v[138:139], v[138:139], v[176:177]
	v_pk_fma_f32 v[176:177], v[140:141], v[140:141], v[176:177]
	v_pk_fma_f32 v[176:177], v[142:143], v[142:143], v[176:177]
	v_cvt_pk_bf16_f32 v160, v136, v137
	v_cvt_pk_bf16_f32 v161, v138, v139
	v_cvt_pk_bf16_f32 v162, v140, v141
	v_cvt_pk_bf16_f32 v163, v142, v143
	global_store_dwordx4 v173, v[160:163], s[16:17] offset:256
	v_add_f32_e32 v178, v176, v177
	s_nop 1
	v_add_f32_dpp v179, v178, v178 quad_perm:[1,0,3,2] row_mask:0xf bank_mask:0xf
	s_nop 1
	v_add_f32_dpp v181, v179, v179 quad_perm:[2,3,0,1] row_mask:0xf bank_mask:0xf
	s_mov_b64 exec, vcc
	global_atomic_add_f32 v174, v181, s[18:19] offset:512
	s_mov_b64 exec, s[8:9]
	v_add_u32_e32 v173, 0x8000, v173
	s_waitcnt lgkmcnt(0)
	ds_read_b128 v[128:131], v171
	ds_read_b128 v[132:135], v172
	ds_read_b128 v[136:139], v171 offset:128
	ds_read_b128 v[140:143], v172 offset:128
	s_waitcnt lgkmcnt(0)
	ds_write_b128 v169, v[28:31]
	ds_write_b128 v170, v[24:27]
	ds_write_b128 v169, v[20:23] offset:128
	ds_write_b128 v170, v[16:19] offset:128
	s_waitcnt vmcnt(17)
	v_pk_add_f32 v[128:129], v[128:129], v[204:205]
	v_pk_add_f32 v[130:131], v[130:131], v[206:207]
	v_pk_add_f32 v[132:133], v[132:133], v[208:209]
	v_pk_add_f32 v[134:135], v[134:135], v[210:211]
	v_pk_mul_f32 v[176:177], v[128:129], v[128:129]
	v_pk_fma_f32 v[176:177], v[130:131], v[130:131], v[176:177]
	v_pk_fma_f32 v[176:177], v[132:133], v[132:133], v[176:177]
	v_pk_fma_f32 v[176:177], v[134:135], v[134:135], v[176:177]
	v_cvt_pk_bf16_f32 v156, v128, v129
	v_cvt_pk_bf16_f32 v157, v130, v131
	v_cvt_pk_bf16_f32 v158, v132, v133
	v_cvt_pk_bf16_f32 v159, v134, v135
	global_store_dwordx4 v173, v[156:159], s[16:17]
	v_pk_add_f32 v[136:137], v[136:137], v[212:213]
	v_pk_add_f32 v[138:139], v[138:139], v[214:215]
	v_pk_add_f32 v[140:141], v[140:141], v[216:217]
	v_pk_add_f32 v[142:143], v[142:143], v[218:219]
	v_pk_fma_f32 v[176:177], v[136:137], v[136:137], v[176:177]
	v_pk_fma_f32 v[176:177], v[138:139], v[138:139], v[176:177]
	v_pk_fma_f32 v[176:177], v[140:141], v[140:141], v[176:177]
	v_pk_fma_f32 v[176:177], v[142:143], v[142:143], v[176:177]
	v_cvt_pk_bf16_f32 v160, v136, v137
	v_cvt_pk_bf16_f32 v161, v138, v139
	v_cvt_pk_bf16_f32 v162, v140, v141
	v_cvt_pk_bf16_f32 v163, v142, v143
	global_store_dwordx4 v173, v[160:163], s[16:17] offset:256
	v_add_f32_e32 v178, v176, v177
	s_nop 1
	v_add_f32_dpp v179, v178, v178 quad_perm:[1,0,3,2] row_mask:0xf bank_mask:0xf
	s_nop 1
	v_add_f32_dpp v181, v179, v179 quad_perm:[2,3,0,1] row_mask:0xf bank_mask:0xf
	s_mov_b64 exec, vcc
	global_atomic_add_f32 v174, v181, s[18:19] offset:576
	s_mov_b64 exec, s[8:9]
	v_add_u32_e32 v173, 0x8000, v173
	s_waitcnt lgkmcnt(0)
	ds_read_b128 v[128:131], v171
	ds_read_b128 v[132:135], v172
	ds_read_b128 v[136:139], v171 offset:128
	ds_read_b128 v[140:143], v172 offset:128
	s_waitcnt lgkmcnt(0)
	ds_write_b128 v169, v[12:15]
	ds_write_b128 v170, v[8:11]
	ds_write_b128 v169, v[4:7] offset:128
	ds_write_b128 v170, v[0:3] offset:128
	s_waitcnt vmcnt(13)
	v_pk_add_f32 v[128:129], v[128:129], v[220:221]
	v_pk_add_f32 v[130:131], v[130:131], v[222:223]
	v_pk_add_f32 v[132:133], v[132:133], v[224:225]
	v_pk_add_f32 v[134:135], v[134:135], v[226:227]
	v_pk_mul_f32 v[176:177], v[128:129], v[128:129]
	v_pk_fma_f32 v[176:177], v[130:131], v[130:131], v[176:177]
	v_pk_fma_f32 v[176:177], v[132:133], v[132:133], v[176:177]
	v_pk_fma_f32 v[176:177], v[134:135], v[134:135], v[176:177]
	v_cvt_pk_bf16_f32 v156, v128, v129
	v_cvt_pk_bf16_f32 v157, v130, v131
	v_cvt_pk_bf16_f32 v158, v132, v133
	v_cvt_pk_bf16_f32 v159, v134, v135
	global_store_dwordx4 v173, v[156:159], s[16:17]
	v_pk_add_f32 v[136:137], v[136:137], v[228:229]
	v_pk_add_f32 v[138:139], v[138:139], v[230:231]
	v_pk_add_f32 v[140:141], v[140:141], v[232:233]
	v_pk_add_f32 v[142:143], v[142:143], v[234:235]
	v_pk_fma_f32 v[176:177], v[136:137], v[136:137], v[176:177]
	v_pk_fma_f32 v[176:177], v[138:139], v[138:139], v[176:177]
	v_pk_fma_f32 v[176:177], v[140:141], v[140:141], v[176:177]
	v_pk_fma_f32 v[176:177], v[142:143], v[142:143], v[176:177]
	v_cvt_pk_bf16_f32 v160, v136, v137
	v_cvt_pk_bf16_f32 v161, v138, v139
	v_cvt_pk_bf16_f32 v162, v140, v141
	v_cvt_pk_bf16_f32 v163, v142, v143
	global_store_dwordx4 v173, v[160:163], s[16:17] offset:256
	v_add_f32_e32 v178, v176, v177
	s_nop 1
	v_add_f32_dpp v179, v178, v178 quad_perm:[1,0,3,2] row_mask:0xf bank_mask:0xf
	s_nop 1
	v_add_f32_dpp v181, v179, v179 quad_perm:[2,3,0,1] row_mask:0xf bank_mask:0xf
	s_mov_b64 exec, vcc
	global_atomic_add_f32 v174, v181, s[18:19] offset:640
	s_mov_b64 exec, s[8:9]
	v_add_u32_e32 v173, 0x8000, v173
	s_waitcnt lgkmcnt(0)
	ds_read_b128 v[128:131], v171
	ds_read_b128 v[132:135], v172
	ds_read_b128 v[136:139], v171 offset:128
	ds_read_b128 v[140:143], v172 offset:128
	s_waitcnt lgkmcnt(0)
	s_waitcnt vmcnt(9)
	v_pk_add_f32 v[128:129], v[128:129], v[236:237]
	v_pk_add_f32 v[130:131], v[130:131], v[238:239]
	v_pk_add_f32 v[132:133], v[132:133], v[240:241]
	v_pk_add_f32 v[134:135], v[134:135], v[242:243]
	v_pk_mul_f32 v[176:177], v[128:129], v[128:129]
	v_pk_fma_f32 v[176:177], v[130:131], v[130:131], v[176:177]
	v_pk_fma_f32 v[176:177], v[132:133], v[132:133], v[176:177]
	v_pk_fma_f32 v[176:177], v[134:135], v[134:135], v[176:177]
	v_cvt_pk_bf16_f32 v156, v128, v129
	v_cvt_pk_bf16_f32 v157, v130, v131
	v_cvt_pk_bf16_f32 v158, v132, v133
	v_cvt_pk_bf16_f32 v159, v134, v135
	global_store_dwordx4 v173, v[156:159], s[16:17]
	v_pk_add_f32 v[136:137], v[136:137], v[244:245]
	v_pk_add_f32 v[138:139], v[138:139], v[246:247]
	v_pk_add_f32 v[140:141], v[140:141], v[248:249]
	v_pk_add_f32 v[142:143], v[142:143], v[250:251]
	v_pk_fma_f32 v[176:177], v[136:137], v[136:137], v[176:177]
	v_pk_fma_f32 v[176:177], v[138:139], v[138:139], v[176:177]
	v_pk_fma_f32 v[176:177], v[140:141], v[140:141], v[176:177]
	v_pk_fma_f32 v[176:177], v[142:143], v[142:143], v[176:177]
	v_cvt_pk_bf16_f32 v160, v136, v137
	v_cvt_pk_bf16_f32 v161, v138, v139
	v_cvt_pk_bf16_f32 v162, v140, v141
	v_cvt_pk_bf16_f32 v163, v142, v143
	global_store_dwordx4 v173, v[160:163], s[16:17] offset:256
	v_add_f32_e32 v178, v176, v177
	s_nop 1
	v_add_f32_dpp v179, v178, v178 quad_perm:[1,0,3,2] row_mask:0xf bank_mask:0xf
	s_nop 1
	v_add_f32_dpp v181, v179, v179 quad_perm:[2,3,0,1] row_mask:0xf bank_mask:0xf
	s_mov_b64 exec, vcc
	global_atomic_add_f32 v174, v181, s[18:19] offset:704
	s_mov_b64 exec, s[8:9]
	s_branch .Lqepi_end_6
